# row-norm loops: wave sums via DPP row reductions instead of 6-step ds_bpermute butterflies; phase-0 gain chunks loaded together
# baseline (speedup 1.0000x reference)
.LBB0_79:
	s_or_b64 exec, exec, s[24:25]
	s_waitcnt vmcnt(0)
	v_pk_mul_f32 v[46:47], v[20:21], v[20:21]
	v_pk_mul_f32 v[48:49], v[22:23], v[22:23]
	v_add_f32_e32 v3, v47, v46
	v_pk_mul_f32 v[50:51], v[24:25], v[24:25]
	v_add_f32_e32 v3, v48, v3
	v_add_f32_e32 v1, v51, v50
	v_add_f32_e32 v3, v49, v3
	global_load_dwordx4 v[48:51], v[38:39], off
	global_load_dwordx4 v[132:135], v[38:39], off offset:1024
	global_load_dwordx4 v[136:139], v[38:39], off offset:2048
	global_load_dwordx4 v[140:143], v[38:39], off offset:3072
	v_pk_mul_f32 v[52:53], v[26:27], v[26:27]
	v_pk_mul_f32 v[54:55], v[28:29], v[28:29]
	v_add_f32_e32 v1, v52, v1
	v_add_f32_e32 v1, v53, v1
	v_pk_mul_f32 v[56:57], v[30:31], v[30:31]
	v_add_f32_e32 v1, v3, v1
	v_add_f32_e32 v3, v55, v54
	v_add_f32_e32 v3, v56, v3
	v_pk_mul_f32 v[58:59], v[32:33], v[32:33]
	v_add_f32_e32 v3, v57, v3
	v_pk_mul_f32 v[60:61], v[34:35], v[34:35]
	v_add_f32_e32 v1, v1, v3
	v_add_f32_e32 v3, v59, v58
	v_add_f32_e32 v3, v60, v3
	v_add_f32_e32 v3, v61, v3
	v_add_f32_e32 v1, v1, v3
	s_mov_b32 s4, 0x800000
	s_nop 1
	v_add_f32_dpp v1, v1, v1 quad_perm:[1,0,3,2] row_mask:0xf bank_mask:0xf
	s_nop 1
	v_add_f32_dpp v1, v1, v1 quad_perm:[2,3,0,1] row_mask:0xf bank_mask:0xf
	s_nop 1
	v_add_f32_dpp v1, v1, v1 row_half_mirror row_mask:0xf bank_mask:0xf
	s_nop 1
	v_add_f32_dpp v1, v1, v1 row_mirror row_mask:0xf bank_mask:0xf
	s_nop 1
	v_add_f32_dpp v1, v1, v1 row_bcast:15 row_mask:0xa bank_mask:0xf
	s_nop 1
	v_add_f32_dpp v1, v1, v1 row_bcast:31 row_mask:0xc bank_mask:0xf
	s_nop 1
	v_readlane_b32 vcc_lo, v1, 63
	s_waitcnt lgkmcnt(0)
	s_nop 1
	v_mov_b32_e32 v1, vcc_lo
	v_fmamk_f32 v1, v1, 0x3a800000, v198
	v_cmp_gt_f32_e32 vcc, s4, v1
	v_mul_f32_e32 v3, 0x4b800000, v1
	s_nop 0
	v_cndmask_b32_e32 v1, v1, v3, vcc
	v_rsq_f32_e32 v1, v1
	s_nop 0
	v_mul_f32_e32 v3, 0x45800000, v1
	v_cndmask_b32_e32 v46, v1, v3, vcc
	v_pk_mul_f32 v[20:21], v[20:21], v[46:47] op_sel_hi:[1,0]
	v_pk_mul_f32 v[24:25], v[24:25], v[46:47] op_sel_hi:[1,0]
	s_waitcnt vmcnt(0)
	v_pk_fma_f32 v[16:17], v[48:49], v[20:21], v[16:17]
	v_pk_mul_f32 v[20:21], v[22:23], v[46:47] op_sel_hi:[1,0]
	s_nop 0
	v_pk_fma_f32 v[18:19], v[50:51], v[20:21], v[18:19]
	v_mov_b64_e32 v[20:21], v[132:133]
	v_mov_b64_e32 v[22:23], v[134:135]
	v_pk_fma_f32 v[12:13], v[20:21], v[24:25], v[12:13]
	v_pk_mul_f32 v[20:21], v[26:27], v[46:47] op_sel_hi:[1,0]
	v_pk_mul_f32 v[24:25], v[28:29], v[46:47] op_sel_hi:[1,0]
	v_pk_fma_f32 v[14:15], v[22:23], v[20:21], v[14:15]
	v_mov_b64_e32 v[20:21], v[136:137]
	v_mov_b64_e32 v[22:23], v[138:139]
	v_pk_fma_f32 v[8:9], v[20:21], v[24:25], v[8:9]
	v_pk_mul_f32 v[20:21], v[30:31], v[46:47] op_sel_hi:[1,0]
	v_pk_mul_f32 v[24:25], v[32:33], v[46:47] op_sel_hi:[1,0]
	v_pk_fma_f32 v[10:11], v[22:23], v[20:21], v[10:11]
	v_mov_b64_e32 v[20:21], v[140:141]
	v_mov_b64_e32 v[22:23], v[142:143]
	v_pk_fma_f32 v[4:5], v[24:25], v[20:21], v[4:5]
	v_pk_mul_f32 v[20:21], v[34:35], v[46:47] op_sel_hi:[1,0]
	s_nop 0
	v_pk_fma_f32 v[6:7], v[20:21], v[22:23], v[6:7]

.LBB0_213:
	s_or_b64 exec, exec, s[22:23]
	s_waitcnt vmcnt(0)
	v_pk_mul_f32 v[50:51], v[20:21], v[20:21]
	v_pk_mul_f32 v[52:53], v[22:23], v[22:23]
	v_add_f32_e32 v50, v51, v50
	v_pk_mul_f32 v[54:55], v[24:25], v[24:25]
	v_add_f32_e32 v50, v52, v50
	v_add_f32_e32 v3, v55, v54
	v_add_f32_e32 v50, v53, v50
	global_load_dwordx4 v[52:55], v[38:39], off
	global_load_dwordx4 v[132:135], v[38:39], off offset:1024
	global_load_dwordx4 v[136:139], v[38:39], off offset:2048
	global_load_dwordx4 v[140:143], v[38:39], off offset:3072
	v_pk_mul_f32 v[56:57], v[26:27], v[26:27]
	v_pk_mul_f32 v[58:59], v[28:29], v[28:29]
	v_add_f32_e32 v3, v56, v3
	v_add_f32_e32 v3, v57, v3
	v_pk_mul_f32 v[60:61], v[30:31], v[30:31]
	v_add_f32_e32 v3, v50, v3
	v_add_f32_e32 v50, v59, v58
	v_add_f32_e32 v50, v60, v50
	v_pk_mul_f32 v[62:63], v[32:33], v[32:33]
	v_add_f32_e32 v50, v61, v50
	v_pk_mul_f32 v[64:65], v[34:35], v[34:35]
	v_add_f32_e32 v3, v3, v50
	v_add_f32_e32 v50, v63, v62
	v_add_f32_e32 v50, v64, v50
	v_add_f32_e32 v50, v65, v50
	v_add_f32_e32 v3, v3, v50
	s_mov_b32 s6, 0x800000
	s_nop 1
	v_add_f32_dpp v3, v3, v3 quad_perm:[1,0,3,2] row_mask:0xf bank_mask:0xf
	s_nop 1
	v_add_f32_dpp v3, v3, v3 quad_perm:[2,3,0,1] row_mask:0xf bank_mask:0xf
	s_nop 1
	v_add_f32_dpp v3, v3, v3 row_half_mirror row_mask:0xf bank_mask:0xf
	s_nop 1
	v_add_f32_dpp v3, v3, v3 row_mirror row_mask:0xf bank_mask:0xf
	s_nop 1
	v_add_f32_dpp v3, v3, v3 row_bcast:15 row_mask:0xa bank_mask:0xf
	s_nop 1
	v_add_f32_dpp v3, v3, v3 row_bcast:31 row_mask:0xc bank_mask:0xf
	s_nop 1
	v_readlane_b32 vcc_lo, v3, 63
	s_waitcnt lgkmcnt(0)
	s_nop 1
	v_mov_b32_e32 v3, vcc_lo
	v_fmamk_f32 v3, v3, 0x3a800000, v198
	v_cmp_gt_f32_e32 vcc, s6, v3
	v_mul_f32_e32 v50, 0x4b800000, v3
	s_nop 0
	v_cndmask_b32_e32 v3, v3, v50, vcc
	v_rsq_f32_e32 v3, v3
	s_nop 0
	v_mul_f32_e32 v50, 0x45800000, v3
	v_cndmask_b32_e32 v50, v3, v50, vcc
	v_pk_mul_f32 v[20:21], v[20:21], v[50:51] op_sel_hi:[1,0]
	v_pk_mul_f32 v[24:25], v[24:25], v[50:51] op_sel_hi:[1,0]
	s_waitcnt vmcnt(0)
	v_pk_fma_f32 v[16:17], v[52:53], v[20:21], v[16:17]
	v_pk_mul_f32 v[20:21], v[22:23], v[50:51] op_sel_hi:[1,0]
	s_nop 0
	v_pk_fma_f32 v[18:19], v[54:55], v[20:21], v[18:19]
	v_mov_b64_e32 v[20:21], v[132:133]
	v_mov_b64_e32 v[22:23], v[134:135]
	v_pk_fma_f32 v[12:13], v[20:21], v[24:25], v[12:13]
	v_pk_mul_f32 v[20:21], v[26:27], v[50:51] op_sel_hi:[1,0]
	v_pk_mul_f32 v[24:25], v[28:29], v[50:51] op_sel_hi:[1,0]
	v_pk_fma_f32 v[14:15], v[22:23], v[20:21], v[14:15]
	v_mov_b64_e32 v[20:21], v[136:137]
	v_mov_b64_e32 v[22:23], v[138:139]
	v_pk_fma_f32 v[8:9], v[20:21], v[24:25], v[8:9]
	v_pk_mul_f32 v[20:21], v[30:31], v[50:51] op_sel_hi:[1,0]
	v_pk_mul_f32 v[24:25], v[32:33], v[50:51] op_sel_hi:[1,0]
	v_pk_fma_f32 v[10:11], v[22:23], v[20:21], v[10:11]
	v_mov_b64_e32 v[20:21], v[140:141]
	v_mov_b64_e32 v[22:23], v[142:143]
	v_pk_fma_f32 v[4:5], v[24:25], v[20:21], v[4:5]
	v_pk_mul_f32 v[20:21], v[34:35], v[50:51] op_sel_hi:[1,0]
	s_nop 0
	v_pk_fma_f32 v[6:7], v[20:21], v[22:23], v[6:7]
.LBB0_214:
	v_readlane_b32 s6, v254, 28
	v_readlane_b32 s7, v254, 29
	s_andn2_b64 vcc, exec, s[6:7]
	s_waitcnt vmcnt(3)
	global_store_dwordx4 v[48:49], v[16:19], off
	s_waitcnt vmcnt(3)
	global_store_dwordx4 v[48:49], v[12:15], off offset:1024
	s_waitcnt vmcnt(3)
	global_store_dwordx4 v[48:49], v[8:11], off offset:2048
	s_waitcnt vmcnt(3)
	global_store_dwordx4 v[48:49], v[4:7], off offset:3072
	s_cbranch_vccnz .LBB0_195
	v_mov_b32_e32 v20, v12
	v_mov_b32_e32 v21, v16
	v_pk_mul_f32 v[20:21], v[20:21], v[20:21]
	v_mov_b32_e32 v22, v13
	v_mov_b32_e32 v23, v17
	v_pk_fma_f32 v[20:21], v[22:23], v[22:23], v[20:21]
	v_mov_b32_e32 v22, v14
	v_mov_b32_e32 v23, v18
	v_pk_fma_f32 v[20:21], v[22:23], v[22:23], v[20:21]
	v_mov_b32_e32 v22, v15
	v_mov_b32_e32 v23, v19
	v_pk_fma_f32 v[20:21], v[22:23], v[22:23], v[20:21]
	v_mov_b32_e32 v22, v4
	v_mov_b32_e32 v23, v8
	v_pk_mul_f32 v[22:23], v[22:23], v[22:23]
	v_mov_b32_e32 v24, v5
	v_mov_b32_e32 v25, v9
	v_pk_fma_f32 v[22:23], v[24:25], v[24:25], v[22:23]
	v_mov_b32_e32 v24, v6
	v_mov_b32_e32 v25, v10
	v_pk_fma_f32 v[22:23], v[24:25], v[24:25], v[22:23]
	v_mov_b32_e32 v24, v7
	v_mov_b32_e32 v25, v11
	v_pk_fma_f32 v[22:23], v[24:25], v[24:25], v[22:23]
	global_load_dwordx4 v[24:27], v[42:43], off
	global_load_dwordx4 v[144:147], v[42:43], off offset:1024
	global_load_dwordx4 v[148:151], v[42:43], off offset:2048
	global_load_dwordx4 v[152:155], v[42:43], off offset:3072
	v_add_f32_e32 v3, v20, v21
	v_add_f32_e32 v3, v23, v3
	v_add_f32_e32 v3, v22, v3
	s_mov_b32 s6, 0x800000
	s_nop 1
	v_add_f32_dpp v3, v3, v3 quad_perm:[1,0,3,2] row_mask:0xf bank_mask:0xf
	s_nop 1
	v_add_f32_dpp v3, v3, v3 quad_perm:[2,3,0,1] row_mask:0xf bank_mask:0xf
	s_nop 1
	v_add_f32_dpp v3, v3, v3 row_half_mirror row_mask:0xf bank_mask:0xf
	s_nop 1
	v_add_f32_dpp v3, v3, v3 row_mirror row_mask:0xf bank_mask:0xf
	s_nop 1
	v_add_f32_dpp v3, v3, v3 row_bcast:15 row_mask:0xa bank_mask:0xf
	s_nop 1
	v_add_f32_dpp v3, v3, v3 row_bcast:31 row_mask:0xc bank_mask:0xf
	s_nop 1
	v_readlane_b32 vcc_lo, v3, 63
	s_waitcnt lgkmcnt(0)
	s_nop 1
	v_mov_b32_e32 v3, vcc_lo
	v_fmamk_f32 v3, v3, 0x3a800000, v198
	v_cmp_gt_f32_e32 vcc, s6, v3
	v_mul_f32_e32 v20, 0x4b800000, v3
	s_nop 0
	v_cndmask_b32_e32 v3, v3, v20, vcc
	v_rsq_f32_e32 v3, v3
	s_nop 0
	v_mul_f32_e32 v20, 0x45800000, v3
	v_cndmask_b32_e32 v22, v3, v20, vcc
	v_pk_mul_f32 v[16:17], v[16:17], v[22:23] op_sel_hi:[1,0]
	v_pk_mul_f32 v[18:19], v[18:19], v[22:23] op_sel_hi:[1,0]
	v_lshlrev_b64 v[20:21], 11, v[0:1]
	s_waitcnt vmcnt(0)
	v_pk_mul_f32 v[16:17], v[24:25], v[16:17]
	v_pk_mul_f32 v[18:19], v[26:27], v[18:19]
	v_lshl_add_u64 v[20:21], v[44:45], 0, v[20:21]
	v_cvt_pk_bf16_f32 v16, v16, v17
	v_cvt_pk_bf16_f32 v17, v18, v19
	global_store_dwordx2 v[20:21], v[16:17], off
	v_mov_b64_e32 v[16:17], v[144:145]
	v_mov_b64_e32 v[18:19], v[146:147]
	v_pk_mul_f32 v[12:13], v[12:13], v[22:23] op_sel_hi:[1,0]
	v_pk_mul_f32 v[14:15], v[14:15], v[22:23] op_sel_hi:[1,0]
	v_pk_mul_f32 v[8:9], v[8:9], v[22:23] op_sel_hi:[1,0]
	v_pk_mul_f32 v[10:11], v[10:11], v[22:23] op_sel_hi:[1,0]
	v_pk_mul_f32 v[4:5], v[4:5], v[22:23] op_sel_hi:[1,0]
	v_pk_mul_f32 v[6:7], v[6:7], v[22:23] op_sel_hi:[1,0]
	v_pk_mul_f32 v[12:13], v[16:17], v[12:13]
	v_pk_mul_f32 v[14:15], v[18:19], v[14:15]
	v_cvt_pk_bf16_f32 v12, v12, v13
	v_cvt_pk_bf16_f32 v13, v14, v15
	global_store_dwordx2 v[20:21], v[12:13], off offset:512
	v_mov_b64_e32 v[12:13], v[148:149]
	v_mov_b64_e32 v[14:15], v[150:151]
	v_pk_mul_f32 v[8:9], v[8:9], v[12:13]
	v_pk_mul_f32 v[10:11], v[10:11], v[14:15]
	v_cvt_pk_bf16_f32 v8, v8, v9
	v_cvt_pk_bf16_f32 v9, v10, v11
	global_store_dwordx2 v[20:21], v[8:9], off offset:1024
	v_mov_b64_e32 v[8:9], v[152:153]
	v_mov_b64_e32 v[10:11], v[154:155]
	v_pk_mul_f32 v[4:5], v[4:5], v[8:9]
	v_pk_mul_f32 v[6:7], v[6:7], v[10:11]
	v_cvt_pk_bf16_f32 v4, v4, v5
	v_cvt_pk_bf16_f32 v5, v6, v7
	global_store_dwordx2 v[20:21], v[4:5], off offset:1536
	s_branch .LBB0_195

.LBB0_988:
	s_or_b64 exec, exec, s[22:23]
	s_waitcnt vmcnt(0)
	v_pk_mul_f32 v[50:51], v[20:21], v[20:21]
	v_pk_mul_f32 v[52:53], v[22:23], v[22:23]
	v_add_f32_e32 v50, v51, v50
	v_pk_mul_f32 v[54:55], v[24:25], v[24:25]
	v_add_f32_e32 v50, v52, v50
	v_add_f32_e32 v3, v55, v54
	v_add_f32_e32 v50, v53, v50
	global_load_dwordx4 v[52:55], v[38:39], off
	global_load_dwordx4 v[132:135], v[38:39], off offset:1024
	global_load_dwordx4 v[136:139], v[38:39], off offset:2048
	global_load_dwordx4 v[140:143], v[38:39], off offset:3072
	v_pk_mul_f32 v[56:57], v[26:27], v[26:27]
	v_pk_mul_f32 v[58:59], v[28:29], v[28:29]
	v_add_f32_e32 v3, v56, v3
	v_add_f32_e32 v3, v57, v3
	v_pk_mul_f32 v[60:61], v[30:31], v[30:31]
	v_add_f32_e32 v3, v50, v3
	v_add_f32_e32 v50, v59, v58
	v_add_f32_e32 v50, v60, v50
	v_pk_mul_f32 v[62:63], v[32:33], v[32:33]
	v_add_f32_e32 v50, v61, v50
	v_pk_mul_f32 v[64:65], v[34:35], v[34:35]
	v_add_f32_e32 v3, v3, v50
	v_add_f32_e32 v50, v63, v62
	v_add_f32_e32 v50, v64, v50
	v_add_f32_e32 v50, v65, v50
	v_add_f32_e32 v3, v3, v50
	s_mov_b32 s4, 0x800000
	s_nop 1
	v_add_f32_dpp v3, v3, v3 quad_perm:[1,0,3,2] row_mask:0xf bank_mask:0xf
	s_nop 1
	v_add_f32_dpp v3, v3, v3 quad_perm:[2,3,0,1] row_mask:0xf bank_mask:0xf
	s_nop 1
	v_add_f32_dpp v3, v3, v3 row_half_mirror row_mask:0xf bank_mask:0xf
	s_nop 1
	v_add_f32_dpp v3, v3, v3 row_mirror row_mask:0xf bank_mask:0xf
	s_nop 1
	v_add_f32_dpp v3, v3, v3 row_bcast:15 row_mask:0xa bank_mask:0xf
	s_nop 1
	v_add_f32_dpp v3, v3, v3 row_bcast:31 row_mask:0xc bank_mask:0xf
	s_nop 1
	v_readlane_b32 vcc_lo, v3, 63
	s_waitcnt lgkmcnt(0)
	s_nop 1
	v_mov_b32_e32 v3, vcc_lo
	v_fmamk_f32 v3, v3, 0x3a800000, v198
	v_cmp_gt_f32_e32 vcc, s4, v3
	v_mul_f32_e32 v50, 0x4b800000, v3
	s_nop 0
	v_cndmask_b32_e32 v3, v3, v50, vcc
	v_rsq_f32_e32 v3, v3
	s_nop 0
	v_mul_f32_e32 v50, 0x45800000, v3
	v_cndmask_b32_e32 v50, v3, v50, vcc
	v_pk_mul_f32 v[20:21], v[20:21], v[50:51] op_sel_hi:[1,0]
	v_pk_mul_f32 v[24:25], v[24:25], v[50:51] op_sel_hi:[1,0]
	s_waitcnt vmcnt(0)
	v_pk_fma_f32 v[16:17], v[52:53], v[20:21], v[16:17]
	v_pk_mul_f32 v[20:21], v[22:23], v[50:51] op_sel_hi:[1,0]
	s_nop 0
	v_pk_fma_f32 v[18:19], v[54:55], v[20:21], v[18:19]
	v_mov_b64_e32 v[20:21], v[132:133]
	v_mov_b64_e32 v[22:23], v[134:135]
	v_pk_fma_f32 v[12:13], v[20:21], v[24:25], v[12:13]
	v_pk_mul_f32 v[20:21], v[26:27], v[50:51] op_sel_hi:[1,0]
	v_pk_mul_f32 v[24:25], v[28:29], v[50:51] op_sel_hi:[1,0]
	v_pk_fma_f32 v[14:15], v[22:23], v[20:21], v[14:15]
	v_mov_b64_e32 v[20:21], v[136:137]
	v_mov_b64_e32 v[22:23], v[138:139]
	v_pk_fma_f32 v[8:9], v[20:21], v[24:25], v[8:9]
	v_pk_mul_f32 v[20:21], v[30:31], v[50:51] op_sel_hi:[1,0]
	v_pk_mul_f32 v[24:25], v[32:33], v[50:51] op_sel_hi:[1,0]
	v_pk_fma_f32 v[10:11], v[22:23], v[20:21], v[10:11]
	v_mov_b64_e32 v[20:21], v[140:141]
	v_mov_b64_e32 v[22:23], v[142:143]
	v_pk_fma_f32 v[4:5], v[24:25], v[20:21], v[4:5]
	v_pk_mul_f32 v[20:21], v[34:35], v[50:51] op_sel_hi:[1,0]
	s_nop 0
	v_pk_fma_f32 v[6:7], v[20:21], v[22:23], v[6:7]
.LBB0_989:
	v_readlane_b32 s4, v254, 28
	v_readlane_b32 s5, v254, 29
	s_andn2_b64 vcc, exec, s[4:5]
	s_waitcnt vmcnt(3)
	global_store_dwordx4 v[48:49], v[16:19], off
	s_waitcnt vmcnt(3)
	global_store_dwordx4 v[48:49], v[12:15], off offset:1024
	s_waitcnt vmcnt(3)
	global_store_dwordx4 v[48:49], v[8:11], off offset:2048
	s_waitcnt vmcnt(3)
	global_store_dwordx4 v[48:49], v[4:7], off offset:3072
	s_cbranch_vccnz .LBB0_970
	v_mov_b32_e32 v20, v12
	v_mov_b32_e32 v21, v16
	v_pk_mul_f32 v[20:21], v[20:21], v[20:21]
	v_mov_b32_e32 v22, v13
	v_mov_b32_e32 v23, v17
	v_pk_fma_f32 v[20:21], v[22:23], v[22:23], v[20:21]
	v_mov_b32_e32 v22, v14
	v_mov_b32_e32 v23, v18
	v_pk_fma_f32 v[20:21], v[22:23], v[22:23], v[20:21]
	v_mov_b32_e32 v22, v15
	v_mov_b32_e32 v23, v19
	v_pk_fma_f32 v[20:21], v[22:23], v[22:23], v[20:21]
	v_mov_b32_e32 v22, v4
	v_mov_b32_e32 v23, v8
	v_pk_mul_f32 v[22:23], v[22:23], v[22:23]
	v_mov_b32_e32 v24, v5
	v_mov_b32_e32 v25, v9
	v_pk_fma_f32 v[22:23], v[24:25], v[24:25], v[22:23]
	v_mov_b32_e32 v24, v6
	v_mov_b32_e32 v25, v10
	v_pk_fma_f32 v[22:23], v[24:25], v[24:25], v[22:23]
	v_mov_b32_e32 v24, v7
	v_mov_b32_e32 v25, v11
	v_pk_fma_f32 v[22:23], v[24:25], v[24:25], v[22:23]
	global_load_dwordx4 v[24:27], v[42:43], off
	global_load_dwordx4 v[144:147], v[42:43], off offset:1024
	global_load_dwordx4 v[148:151], v[42:43], off offset:2048
	global_load_dwordx4 v[152:155], v[42:43], off offset:3072
	v_add_f32_e32 v3, v20, v21
	v_add_f32_e32 v3, v23, v3
	v_add_f32_e32 v3, v22, v3
	s_mov_b32 s4, 0x800000
	s_nop 1
	v_add_f32_dpp v3, v3, v3 quad_perm:[1,0,3,2] row_mask:0xf bank_mask:0xf
	s_nop 1
	v_add_f32_dpp v3, v3, v3 quad_perm:[2,3,0,1] row_mask:0xf bank_mask:0xf
	s_nop 1
	v_add_f32_dpp v3, v3, v3 row_half_mirror row_mask:0xf bank_mask:0xf
	s_nop 1
	v_add_f32_dpp v3, v3, v3 row_mirror row_mask:0xf bank_mask:0xf
	s_nop 1
	v_add_f32_dpp v3, v3, v3 row_bcast:15 row_mask:0xa bank_mask:0xf
	s_nop 1
	v_add_f32_dpp v3, v3, v3 row_bcast:31 row_mask:0xc bank_mask:0xf
	s_nop 1
	v_readlane_b32 vcc_lo, v3, 63
	s_waitcnt lgkmcnt(0)
	s_nop 1
	v_mov_b32_e32 v3, vcc_lo
	v_fmamk_f32 v3, v3, 0x3a800000, v198
	v_cmp_gt_f32_e32 vcc, s4, v3
	v_mul_f32_e32 v20, 0x4b800000, v3
	s_nop 0
	v_cndmask_b32_e32 v3, v3, v20, vcc
	v_rsq_f32_e32 v3, v3
	s_nop 0
	v_mul_f32_e32 v20, 0x45800000, v3
	v_cndmask_b32_e32 v22, v3, v20, vcc
	v_pk_mul_f32 v[16:17], v[16:17], v[22:23] op_sel_hi:[1,0]
	v_pk_mul_f32 v[18:19], v[18:19], v[22:23] op_sel_hi:[1,0]
	v_lshlrev_b64 v[20:21], 11, v[0:1]
	s_waitcnt vmcnt(0)
	v_pk_mul_f32 v[16:17], v[24:25], v[16:17]
	v_pk_mul_f32 v[18:19], v[26:27], v[18:19]
	v_lshl_add_u64 v[20:21], v[44:45], 0, v[20:21]
	v_cvt_pk_bf16_f32 v16, v16, v17
	v_cvt_pk_bf16_f32 v17, v18, v19
	global_store_dwordx2 v[20:21], v[16:17], off
	v_mov_b64_e32 v[16:17], v[144:145]
	v_mov_b64_e32 v[18:19], v[146:147]
	v_pk_mul_f32 v[12:13], v[12:13], v[22:23] op_sel_hi:[1,0]
	v_pk_mul_f32 v[14:15], v[14:15], v[22:23] op_sel_hi:[1,0]
	v_pk_mul_f32 v[8:9], v[8:9], v[22:23] op_sel_hi:[1,0]
	v_pk_mul_f32 v[10:11], v[10:11], v[22:23] op_sel_hi:[1,0]
	v_pk_mul_f32 v[4:5], v[4:5], v[22:23] op_sel_hi:[1,0]
	v_pk_mul_f32 v[6:7], v[6:7], v[22:23] op_sel_hi:[1,0]
	v_pk_mul_f32 v[12:13], v[16:17], v[12:13]
	v_pk_mul_f32 v[14:15], v[18:19], v[14:15]
	v_cvt_pk_bf16_f32 v12, v12, v13
	v_cvt_pk_bf16_f32 v13, v14, v15
	global_store_dwordx2 v[20:21], v[12:13], off offset:512
	v_mov_b64_e32 v[12:13], v[148:149]
	v_mov_b64_e32 v[14:15], v[150:151]
	v_pk_mul_f32 v[8:9], v[8:9], v[12:13]
	v_pk_mul_f32 v[10:11], v[10:11], v[14:15]
	v_cvt_pk_bf16_f32 v8, v8, v9
	v_cvt_pk_bf16_f32 v9, v10, v11
	global_store_dwordx2 v[20:21], v[8:9], off offset:1024
	v_mov_b64_e32 v[8:9], v[152:153]
	v_mov_b64_e32 v[10:11], v[154:155]
	v_pk_mul_f32 v[4:5], v[4:5], v[8:9]
	v_pk_mul_f32 v[6:7], v[6:7], v[10:11]
	v_cvt_pk_bf16_f32 v4, v4, v5
	v_cvt_pk_bf16_f32 v5, v6, v7
	global_store_dwordx2 v[20:21], v[4:5], off offset:1536
	s_branch .LBB0_970

.LBB0_997:
	v_add_u32_e32 v3, 0xffffc000, v0
	v_cmp_gt_i32_e32 vcc, s55, v0
	v_ashrrev_i32_e32 v1, 31, v0
	v_mov_b32_e32 v6, s57
	v_cndmask_b32_e32 v4, v3, v0, vcc
	v_mov_b32_e32 v3, s59
	v_cndmask_b32_e32 v5, 0, v1, vcc
	v_cndmask_b32_e32 v7, v3, v6, vcc
	v_mov_b32_e32 v3, s58
	v_mov_b32_e32 v6, s56
	v_cndmask_b32_e32 v6, v3, v6, vcc
	v_lshlrev_b64 v[4:5], 12, v[4:5]
	v_lshl_add_u64 v[4:5], v[6:7], 0, v[4:5]
	v_mov_b32_e32 v27, v2
	v_lshl_add_u64 v[4:5], v[4:5], 0, v[26:27]
	global_load_dwordx4 v[16:19], v[4:5], off
	global_load_dwordx4 v[12:15], v[4:5], off offset:1024
	global_load_dwordx4 v[8:11], v[4:5], off offset:2048
	s_nop 0
	global_load_dwordx4 v[4:7], v[4:5], off offset:3072
	v_readlane_b32 s4, v254, 28
	v_lshlrev_b64 v[28:29], 12, v[0:1]
	v_readlane_b32 s5, v254, 29
	v_lshl_add_u64 v[28:29], v[20:21], 0, v[28:29]
	s_andn2_b64 vcc, exec, s[4:5]
	s_waitcnt vmcnt(3)
	global_store_dwordx4 v[28:29], v[16:19], off
	s_waitcnt vmcnt(3)
	global_store_dwordx4 v[28:29], v[12:15], off offset:1024
	s_waitcnt vmcnt(3)
	global_store_dwordx4 v[28:29], v[8:11], off offset:2048
	s_waitcnt vmcnt(3)
	global_store_dwordx4 v[28:29], v[4:7], off offset:3072
	s_cbranch_vccnz .LBB0_996
	v_mov_b32_e32 v30, v17
	v_mov_b32_e32 v31, v13
	v_mov_b32_e32 v28, v16
	v_mov_b32_e32 v29, v12
	v_pk_mul_f32 v[30:31], v[30:31], v[30:31]
	v_mov_b32_e32 v32, v9
	v_pk_fma_f32 v[28:29], v[28:29], v[28:29], v[30:31]
	v_mov_b32_e32 v30, v18
	v_mov_b32_e32 v31, v14
	v_pk_fma_f32 v[28:29], v[30:31], v[30:31], v[28:29]
	v_mov_b32_e32 v30, v19
	v_mov_b32_e32 v31, v15
	v_mov_b32_e32 v33, v5
	v_pk_fma_f32 v[28:29], v[30:31], v[30:31], v[28:29]
	v_mov_b32_e32 v30, v8
	v_mov_b32_e32 v31, v4
	v_pk_mul_f32 v[32:33], v[32:33], v[32:33]
	v_pk_fma_f32 v[30:31], v[30:31], v[30:31], v[32:33]
	v_mov_b32_e32 v32, v10
	v_mov_b32_e32 v33, v6
	v_pk_fma_f32 v[30:31], v[32:33], v[32:33], v[30:31]
	v_mov_b32_e32 v32, v11
	v_mov_b32_e32 v33, v7
	v_pk_fma_f32 v[30:31], v[32:33], v[32:33], v[30:31]
	global_load_dwordx4 v[32:35], v[22:23], off
	global_load_dwordx4 v[144:147], v[22:23], off offset:1024
	global_load_dwordx4 v[148:151], v[22:23], off offset:2048
	global_load_dwordx4 v[152:155], v[22:23], off offset:3072
	v_add_f32_e32 v3, v28, v29
	v_add_f32_e32 v3, v3, v30
	v_add_f32_e32 v3, v3, v31
	s_mov_b32 s4, 0x800000
	v_lshlrev_b64 v[28:29], 11, v[0:1]
	v_lshl_add_u64 v[28:29], v[24:25], 0, v[28:29]
	s_nop 1
	v_add_f32_dpp v3, v3, v3 quad_perm:[1,0,3,2] row_mask:0xf bank_mask:0xf
	s_nop 1
	v_add_f32_dpp v3, v3, v3 quad_perm:[2,3,0,1] row_mask:0xf bank_mask:0xf
	s_nop 1
	v_add_f32_dpp v3, v3, v3 row_half_mirror row_mask:0xf bank_mask:0xf
	s_nop 1
	v_add_f32_dpp v3, v3, v3 row_mirror row_mask:0xf bank_mask:0xf
	s_nop 1
	v_add_f32_dpp v3, v3, v3 row_bcast:15 row_mask:0xa bank_mask:0xf
	s_nop 1
	v_add_f32_dpp v3, v3, v3 row_bcast:31 row_mask:0xc bank_mask:0xf
	s_nop 1
	v_readlane_b32 vcc_lo, v3, 63
	s_waitcnt lgkmcnt(0)
	s_nop 1
	v_mov_b32_e32 v3, vcc_lo
	v_fmamk_f32 v3, v3, 0x3a800000, v198
	v_cmp_gt_f32_e32 vcc, s4, v3
	v_mul_f32_e32 v27, 0x4b800000, v3
	s_nop 0
	v_cndmask_b32_e32 v3, v3, v27, vcc
	v_rsq_f32_e32 v3, v3
	s_nop 0
	v_mul_f32_e32 v27, 0x45800000, v3
	v_cndmask_b32_e32 v30, v3, v27, vcc
	v_pk_mul_f32 v[16:17], v[16:17], v[30:31] op_sel_hi:[1,0]
	v_pk_mul_f32 v[18:19], v[18:19], v[30:31] op_sel_hi:[1,0]
	s_waitcnt vmcnt(0)
	v_pk_mul_f32 v[16:17], v[32:33], v[16:17]
	v_pk_mul_f32 v[18:19], v[34:35], v[18:19]
	v_cvt_pk_bf16_f32 v16, v16, v17
	v_cvt_pk_bf16_f32 v17, v18, v19
	global_store_dwordx2 v[28:29], v[16:17], off
	v_mov_b64_e32 v[16:17], v[144:145]
	v_mov_b64_e32 v[18:19], v[146:147]
	v_pk_mul_f32 v[12:13], v[12:13], v[30:31] op_sel_hi:[1,0]
	v_pk_mul_f32 v[14:15], v[14:15], v[30:31] op_sel_hi:[1,0]
	v_pk_mul_f32 v[8:9], v[8:9], v[30:31] op_sel_hi:[1,0]
	v_pk_mul_f32 v[10:11], v[10:11], v[30:31] op_sel_hi:[1,0]
	v_pk_mul_f32 v[4:5], v[4:5], v[30:31] op_sel_hi:[1,0]
	v_pk_mul_f32 v[6:7], v[6:7], v[30:31] op_sel_hi:[1,0]
	v_pk_mul_f32 v[12:13], v[16:17], v[12:13]
	v_pk_mul_f32 v[14:15], v[18:19], v[14:15]
	v_cvt_pk_bf16_f32 v12, v12, v13
	v_cvt_pk_bf16_f32 v13, v14, v15
	global_store_dwordx2 v[28:29], v[12:13], off offset:512
	v_mov_b64_e32 v[12:13], v[148:149]
	v_mov_b64_e32 v[14:15], v[150:151]
	v_pk_mul_f32 v[8:9], v[8:9], v[12:13]
	v_pk_mul_f32 v[10:11], v[10:11], v[14:15]
	v_cvt_pk_bf16_f32 v8, v8, v9
	v_cvt_pk_bf16_f32 v9, v10, v11
	global_store_dwordx2 v[28:29], v[8:9], off offset:1024
	v_mov_b64_e32 v[8:9], v[152:153]
	v_mov_b64_e32 v[10:11], v[154:155]
	v_pk_mul_f32 v[4:5], v[4:5], v[8:9]
	v_pk_mul_f32 v[6:7], v[6:7], v[10:11]
	v_cvt_pk_bf16_f32 v4, v4, v5
	v_cvt_pk_bf16_f32 v5, v6, v7
	global_store_dwordx2 v[28:29], v[4:5], off offset:1536
	s_branch .LBB0_996
